# attention gather indices via v_readlane + scalar address math (16 ds_bpermute per sub-block removed), saddr loads; softmax max-reduce via permlane16/32 swaps
# speedup vs baseline: 1.0076x; 1.0048x over previous
.LBB0_135:
	s_and_b32 s0, s76, 0x7ffff000
	s_mov_b32 s1, s77
	s_lshl_b64 s[0:1], s[0:1], 9
	v_mov_b32_e32 v72, 0
	s_and_b32 s29, s76, 0xfff
	v_mad_u64_u32 v[106:107], s[2:3], s76, v188, v[100:101]
	v_lshl_add_u64 v[108:109], v[102:103], 0, s[0:1]
	v_mov_b32_e32 v128, 0xff800000
	global_load_dwordx4 v[196:199], v[106:107], off
	global_load_dwordx4 v[200:203], v[106:107], off offset:64
	global_load_dwordx4 v[204:207], v[106:107], off offset:128
	global_load_dwordx4 v[208:211], v[106:107], off offset:192
	global_load_dwordx4 v[212:215], v[106:107], off offset:256
	global_load_dwordx4 v[216:219], v[106:107], off offset:320
	global_load_dwordx4 v[220:223], v[106:107], off offset:384
	global_load_dwordx4 v[224:227], v[106:107], off offset:448
	s_mov_b32 s30, 0
	v_mov_b32_e32 v68, 0
	v_mov_b32_e32 v69, v72
	v_mov_b32_e32 v70, v72
	v_mov_b32_e32 v71, v72
	v_mov_b32_e32 v24, 0
	v_mov_b32_e32 v25, v72
	v_mov_b32_e32 v26, v72
	v_mov_b32_e32 v27, v72
	v_mov_b32_e32 v64, 0
	v_mov_b32_e32 v65, v72
	v_mov_b32_e32 v66, v72
	v_mov_b32_e32 v67, v72
	v_mov_b32_e32 v60, 0
	v_mov_b32_e32 v61, v72
	v_mov_b32_e32 v62, v72
	v_mov_b32_e32 v63, v72
	v_mov_b32_e32 v56, 0
	v_mov_b32_e32 v57, v72
	v_mov_b32_e32 v58, v72
	v_mov_b32_e32 v59, v72
	v_mov_b32_e32 v52, 0
	v_mov_b32_e32 v53, v72
	v_mov_b32_e32 v54, v72
	v_mov_b32_e32 v55, v72
	v_mov_b32_e32 v48, 0
	v_mov_b32_e32 v49, v72
	v_mov_b32_e32 v50, v72
	v_mov_b32_e32 v51, v72
	v_mov_b32_e32 v44, 0
	v_mov_b32_e32 v45, v72
	v_mov_b32_e32 v46, v72
	v_mov_b32_e32 v47, v72
	v_mov_b32_e32 v40, 0
	v_mov_b32_e32 v41, v72
	v_mov_b32_e32 v42, v72
	v_mov_b32_e32 v43, v72
	v_mov_b32_e32 v28, 0
	v_mov_b32_e32 v29, v72
	v_mov_b32_e32 v30, v72
	v_mov_b32_e32 v31, v72
	v_mov_b32_e32 v20, 0
	v_mov_b32_e32 v21, v72
	v_mov_b32_e32 v22, v72
	v_mov_b32_e32 v23, v72
	v_mov_b32_e32 v16, 0
	v_mov_b32_e32 v17, v72
	v_mov_b32_e32 v18, v72
	v_mov_b32_e32 v19, v72
	v_mov_b32_e32 v12, 0
	v_mov_b32_e32 v13, v72
	v_mov_b32_e32 v14, v72
	v_mov_b32_e32 v15, v72
	v_mov_b32_e32 v8, 0
	v_mov_b32_e32 v9, v72
	v_mov_b32_e32 v10, v72
	v_mov_b32_e32 v11, v72
	v_mov_b32_e32 v4, 0
	v_mov_b32_e32 v5, v72
	v_mov_b32_e32 v6, v72
	v_mov_b32_e32 v7, v72
	v_mov_b32_e32 v0, 0
	v_mov_b32_e32 v1, v72
	v_mov_b32_e32 v2, v72
	v_mov_b32_e32 v3, v72
	v_mov_b32_e32 v244, v124
	v_readfirstlane_b32 s2, v108
	v_readfirstlane_b32 s3, v109
	v_and_b32_e32 v246, 31, v165
	v_lshlrev_b32_e32 v246, 4, v246
	s_nop 1
	v_readlane_b32 s0, v244, 0
	v_readlane_b32 s1, v244, 1
	v_readlane_b32 vcc_lo, v244, 2
	v_readlane_b32 vcc_hi, v244, 3
	s_max_i32 s0, s0, 0
	s_max_i32 s1, s1, 0
	s_max_i32 vcc_lo, vcc_lo, 0
	s_max_i32 vcc_hi, vcc_hi, 0
	s_sub_i32 s1, s1, s0
	s_sub_i32 vcc_hi, vcc_hi, vcc_lo
	s_lshl_b32 s0, s0, 9
	s_lshl_b32 s1, s1, 9
	s_lshl_b32 vcc_lo, vcc_lo, 9
	s_lshl_b32 vcc_hi, vcc_hi, 9
	v_add_u32_e32 v88, s0, v246
	v_add_u32_e32 v92, vcc_lo, v246
	v_mad_i32_i24 v88, v115, s1, v88
	v_mad_i32_i24 v92, v115, vcc_hi, v92
	global_load_dwordx4 v[88:91], v88, s[2:3]
	global_load_dwordx4 v[92:95], v92, s[2:3]
	v_readlane_b32 s0, v244, 4
	v_readlane_b32 s1, v244, 5
	v_readlane_b32 vcc_lo, v244, 6
	v_readlane_b32 vcc_hi, v244, 7
	s_max_i32 s0, s0, 0
	s_max_i32 s1, s1, 0
	s_max_i32 vcc_lo, vcc_lo, 0
	s_max_i32 vcc_hi, vcc_hi, 0
	s_sub_i32 s1, s1, s0
	s_sub_i32 vcc_hi, vcc_hi, vcc_lo
	s_lshl_b32 s0, s0, 9
	s_lshl_b32 s1, s1, 9
	s_lshl_b32 vcc_lo, vcc_lo, 9
	s_lshl_b32 vcc_hi, vcc_hi, 9
	v_add_u32_e32 v96, s0, v246
	v_add_u32_e32 v144, vcc_lo, v246
	v_mad_i32_i24 v96, v115, s1, v96
	v_mad_i32_i24 v144, v115, vcc_hi, v144
	global_load_dwordx4 v[96:99], v96, s[2:3]
	global_load_dwordx4 v[144:147], v144, s[2:3]
	v_readlane_b32 s0, v244, 8
	v_readlane_b32 s1, v244, 9
	v_readlane_b32 vcc_lo, v244, 10
	v_readlane_b32 vcc_hi, v244, 11
	s_max_i32 s0, s0, 0
	s_max_i32 s1, s1, 0
	s_max_i32 vcc_lo, vcc_lo, 0
	s_max_i32 vcc_hi, vcc_hi, 0
	s_sub_i32 s1, s1, s0
	s_sub_i32 vcc_hi, vcc_hi, vcc_lo
	s_lshl_b32 s0, s0, 9
	s_lshl_b32 s1, s1, 9
	s_lshl_b32 vcc_lo, vcc_lo, 9
	s_lshl_b32 vcc_hi, vcc_hi, 9
	v_add_u32_e32 v152, s0, v246
	v_add_u32_e32 v156, vcc_lo, v246
	v_mad_i32_i24 v152, v115, s1, v152
	v_mad_i32_i24 v156, v115, vcc_hi, v156
	global_load_dwordx4 v[152:155], v152, s[2:3]
	global_load_dwordx4 v[156:159], v156, s[2:3]
	v_readlane_b32 s0, v244, 12
	v_readlane_b32 s1, v244, 13
	v_readlane_b32 vcc_lo, v244, 14
	v_readlane_b32 vcc_hi, v244, 15
	s_max_i32 s0, s0, 0
	s_max_i32 s1, s1, 0
	s_max_i32 vcc_lo, vcc_lo, 0
	s_max_i32 vcc_hi, vcc_hi, 0
	s_sub_i32 s1, s1, s0
	s_sub_i32 vcc_hi, vcc_hi, vcc_lo
	s_lshl_b32 s0, s0, 9
	s_lshl_b32 s1, s1, 9
	s_lshl_b32 vcc_lo, vcc_lo, 9
	s_lshl_b32 vcc_hi, vcc_hi, 9
	v_add_u32_e32 v160, s0, v246
	v_add_u32_e32 v172, vcc_lo, v246
	v_mad_i32_i24 v160, v115, s1, v160
	v_mad_i32_i24 v172, v115, vcc_hi, v172
	global_load_dwordx4 v[160:163], v160, s[2:3]
	global_load_dwordx4 v[172:175], v172, s[2:3]
	v_readlane_b32 s0, v244, 16
	v_readlane_b32 s1, v244, 17
	v_readlane_b32 vcc_lo, v244, 18
	v_readlane_b32 vcc_hi, v244, 19
	s_max_i32 s0, s0, 0
	s_max_i32 s1, s1, 0
	s_max_i32 vcc_lo, vcc_lo, 0
	s_max_i32 vcc_hi, vcc_hi, 0
	s_sub_i32 s1, s1, s0
	s_sub_i32 vcc_hi, vcc_hi, vcc_lo
	s_lshl_b32 s0, s0, 9
	s_lshl_b32 s1, s1, 9
	s_lshl_b32 vcc_lo, vcc_lo, 9
	s_lshl_b32 vcc_hi, vcc_hi, 9
	v_add_u32_e32 v192, s0, v246
	v_add_u32_e32 v132, vcc_lo, v246
	v_mad_i32_i24 v192, v115, s1, v192
	v_mad_i32_i24 v132, v115, vcc_hi, v132
	global_load_dwordx4 v[192:195], v192, s[2:3]
	global_load_dwordx4 v[132:135], v132, s[2:3]
	v_readlane_b32 s0, v244, 20
	v_readlane_b32 s1, v244, 21
	v_readlane_b32 vcc_lo, v244, 22
	v_readlane_b32 vcc_hi, v244, 23
	s_max_i32 s0, s0, 0
	s_max_i32 s1, s1, 0
	s_max_i32 vcc_lo, vcc_lo, 0
	s_max_i32 vcc_hi, vcc_hi, 0
	s_sub_i32 s1, s1, s0
	s_sub_i32 vcc_hi, vcc_hi, vcc_lo
	s_lshl_b32 s0, s0, 9
	s_lshl_b32 s1, s1, 9
	s_lshl_b32 vcc_lo, vcc_lo, 9
	s_lshl_b32 vcc_hi, vcc_hi, 9
	v_add_u32_e32 v136, s0, v246
	v_add_u32_e32 v140, vcc_lo, v246
	v_mad_i32_i24 v136, v115, s1, v136
	v_mad_i32_i24 v140, v115, vcc_hi, v140
	global_load_dwordx4 v[136:139], v136, s[2:3]
	global_load_dwordx4 v[140:143], v140, s[2:3]
	v_readlane_b32 s0, v244, 24
	v_readlane_b32 s1, v244, 25
	v_readlane_b32 vcc_lo, v244, 26
	v_readlane_b32 vcc_hi, v244, 27
	s_max_i32 s0, s0, 0
	s_max_i32 s1, s1, 0
	s_max_i32 vcc_lo, vcc_lo, 0
	s_max_i32 vcc_hi, vcc_hi, 0
	s_sub_i32 s1, s1, s0
	s_sub_i32 vcc_hi, vcc_hi, vcc_lo
	s_lshl_b32 s0, s0, 9
	s_lshl_b32 s1, s1, 9
	s_lshl_b32 vcc_lo, vcc_lo, 9
	s_lshl_b32 vcc_hi, vcc_hi, 9
	v_add_u32_e32 v228, s0, v246
	v_add_u32_e32 v232, vcc_lo, v246
	v_mad_i32_i24 v228, v115, s1, v228
	v_mad_i32_i24 v232, v115, vcc_hi, v232
	global_load_dwordx4 v[228:231], v228, s[2:3]
	global_load_dwordx4 v[232:235], v232, s[2:3]
	v_readlane_b32 s0, v244, 28
	v_readlane_b32 s1, v244, 29
	v_readlane_b32 vcc_lo, v244, 30
	v_readlane_b32 vcc_hi, v244, 31
	s_max_i32 s0, s0, 0
	s_max_i32 s1, s1, 0
	s_max_i32 vcc_lo, vcc_lo, 0
	s_max_i32 vcc_hi, vcc_hi, 0
	s_sub_i32 s1, s1, s0
	s_sub_i32 vcc_hi, vcc_hi, vcc_lo
	s_lshl_b32 s0, s0, 9
	s_lshl_b32 s1, s1, 9
	s_lshl_b32 vcc_lo, vcc_lo, 9
	s_lshl_b32 vcc_hi, vcc_hi, 9
	v_add_u32_e32 v236, s0, v246
	v_add_u32_e32 v240, vcc_lo, v246
	v_mad_i32_i24 v236, v115, s1, v236
	v_mad_i32_i24 v240, v115, vcc_hi, v240
	global_load_dwordx4 v[236:239], v236, s[2:3]
	global_load_dwordx4 v[240:243], v240, s[2:3]
.LBB0_136:
	s_lshr_b32 s2, s30, 1
	s_cmp_lt_u32 s30, 2
	s_cselect_b64 vcc, -1, 0
	s_cmp_eq_u32 s2, 1
	s_cselect_b64 s[0:1], -1, 0
	s_cmp_eq_u32 s2, 2
	s_cselect_b64 s[2:3], -1, 0
	v_mov_b32_e32 v129, v72
	v_cndmask_b32_e64 v72, v127, v126, s[2:3]
	v_cndmask_b32_e64 v72, v72, v125, s[0:1]
	s_and_b32 s0, s28, 32
	v_cndmask_b32_e32 v130, v72, v124, vcc
	s_waitcnt vmcnt(15)
	ds_write_b128 v117, v[88:91]
	s_waitcnt vmcnt(14)
	ds_write_b128 v117, v[92:95] offset:1056
	s_waitcnt vmcnt(13)
	ds_write_b128 v117, v[96:99] offset:2112
	s_waitcnt vmcnt(12)
	ds_write_b128 v117, v[144:147] offset:3168
	s_waitcnt vmcnt(11)
	ds_write_b128 v117, v[152:155] offset:4224
	s_waitcnt vmcnt(10)
	ds_write_b128 v117, v[156:159] offset:5280
	s_waitcnt vmcnt(9)
	ds_write_b128 v117, v[160:163] offset:6336
	s_waitcnt vmcnt(8)
	ds_write_b128 v117, v[172:175] offset:7392
	s_waitcnt vmcnt(7)
	ds_write_b128 v117, v[192:195] offset:8448
	s_waitcnt vmcnt(6)
	ds_write_b128 v117, v[132:135] offset:9504
	s_waitcnt vmcnt(5)
	ds_write_b128 v117, v[136:139] offset:10560
	s_waitcnt vmcnt(4)
	ds_write_b128 v117, v[140:143] offset:11616
	s_waitcnt vmcnt(3)
	ds_write_b128 v117, v[228:231] offset:12672
	s_waitcnt vmcnt(2)
	ds_write_b128 v117, v[232:235] offset:13728
	s_waitcnt vmcnt(1)
	ds_write_b128 v117, v[236:239] offset:14784
	s_waitcnt vmcnt(0)
	ds_write_b128 v117, v[240:243] offset:15840
	v_or_b32_e32 v72, s0, v33
	v_or_b32_e32 v73, v72, v180
	v_lshlrev_b32_e32 v73, 2, v73
	ds_bpermute_b32 v138, v73, v130
	v_or_b32_e32 v73, v72, v110
	v_lshlrev_b32_e32 v73, 2, v73
	ds_bpermute_b32 v139, v73, v130
	v_or_b32_e32 v73, v72, v111
	v_lshlrev_b32_e32 v73, 2, v73
	ds_bpermute_b32 v140, v73, v130
	v_or_b32_e32 v73, v72, v112
	v_lshlrev_b32_e32 v73, 2, v73
	v_or_b32_e32 v72, 16, v72
	ds_bpermute_b32 v141, v73, v130
	v_or_b32_e32 v73, v72, v180
	v_lshlrev_b32_e32 v73, 2, v73
	ds_bpermute_b32 v142, v73, v130
	v_or_b32_e32 v73, v72, v110
	v_lshlrev_b32_e32 v73, 2, v73
	ds_bpermute_b32 v143, v73, v130
	v_or_b32_e32 v73, v72, v111
	v_or_b32_e32 v72, v72, v112
	v_lshlrev_b32_e32 v73, 2, v73
	v_lshlrev_b32_e32 v72, 2, v72
	s_mov_b64 s[0:1], 0
	ds_bpermute_b32 v148, v73, v130
	ds_bpermute_b32 v149, v72, v130
	s_waitcnt lgkmcnt(7)
	v_cmp_lt_i32_e32 vcc, -1, v138
	s_waitcnt lgkmcnt(0)
	ds_read_b128 v[228:231], v118
	ds_read_b128 v[232:235], v118 offset:64
	ds_read_b128 v[236:239], v118 offset:128
	ds_read_b128 v[240:243], v118 offset:192
	s_waitcnt lgkmcnt(3)
	v_mfma_f32_16x16x32_bf16 v[134:137], v[228:231], v[196:199], 0
	ds_read_b128 v[228:231], v118 offset:256
	s_waitcnt lgkmcnt(3)
	v_mfma_f32_16x16x32_bf16 v[134:137], v[232:235], v[200:203], v[134:137]
	ds_read_b128 v[232:235], v118 offset:320
	s_waitcnt lgkmcnt(3)
	v_mfma_f32_16x16x32_bf16 v[134:137], v[236:239], v[204:207], v[134:137]
	ds_read_b128 v[236:239], v118 offset:384
	s_waitcnt lgkmcnt(3)
	v_mfma_f32_16x16x32_bf16 v[134:137], v[240:243], v[208:211], v[134:137]
	ds_read_b128 v[240:243], v118 offset:448
	s_waitcnt lgkmcnt(3)
	v_mfma_f32_16x16x32_bf16 v[134:137], v[228:231], v[212:215], v[134:137]
	ds_read_b128 v[228:231], v118 offset:8448
	s_waitcnt lgkmcnt(3)
	v_mfma_f32_16x16x32_bf16 v[134:137], v[232:235], v[216:219], v[134:137]
	ds_read_b128 v[232:235], v118 offset:8512
	s_waitcnt lgkmcnt(3)
	v_mfma_f32_16x16x32_bf16 v[134:137], v[236:239], v[220:223], v[134:137]
	ds_read_b128 v[236:239], v118 offset:8576
	s_waitcnt lgkmcnt(3)
	v_mfma_f32_16x16x32_bf16 v[134:137], v[240:243], v[224:227], v[134:137]
	ds_read_b128 v[240:243], v118 offset:8640
	s_waitcnt lgkmcnt(3)
	v_mfma_f32_16x16x32_bf16 v[72:75], v[228:231], v[196:199], 0
	ds_read_b128 v[228:231], v118 offset:8704
	s_waitcnt lgkmcnt(3)
	v_mfma_f32_16x16x32_bf16 v[72:75], v[232:235], v[200:203], v[72:75]
	ds_read_b128 v[232:235], v118 offset:8768
	s_waitcnt lgkmcnt(3)
	v_mfma_f32_16x16x32_bf16 v[72:75], v[236:239], v[204:207], v[72:75]
	ds_read_b128 v[236:239], v118 offset:8832
	s_waitcnt lgkmcnt(3)
	v_mfma_f32_16x16x32_bf16 v[72:75], v[240:243], v[208:211], v[72:75]
	ds_read_b128 v[240:243], v118 offset:8896
	v_subrev_u32_e32 v80, s29, v142
	v_med3_i32 v80, v80, s4, v189
	v_lshl_add_u32 v80, v80, 6, v116
	ds_read_b32 v80, v80 offset:8192
	s_waitcnt lgkmcnt(4)
	v_mfma_f32_16x16x32_bf16 v[72:75], v[228:231], v[212:215], v[72:75]
	s_waitcnt lgkmcnt(3)
	v_mfma_f32_16x16x32_bf16 v[72:75], v[232:235], v[216:219], v[72:75]
	s_waitcnt lgkmcnt(2)
	v_mfma_f32_16x16x32_bf16 v[72:75], v[236:239], v[220:223], v[72:75]
	s_waitcnt lgkmcnt(1)
	v_mfma_f32_16x16x32_bf16 v[72:75], v[240:243], v[224:227], v[72:75]
	v_subrev_u32_e32 v76, s29, v138
	v_med3_i32 v76, v76, s4, v189
	v_subrev_u32_e32 v77, s29, v139
	v_lshl_add_u32 v76, v76, 6, v116
	v_med3_i32 v77, v77, s4, v189
	v_subrev_u32_e32 v78, s29, v140
	ds_read_b32 v76, v76 offset:8192
	v_lshl_add_u32 v77, v77, 6, v116
	v_med3_i32 v78, v78, s4, v189
	v_subrev_u32_e32 v79, s29, v141
	ds_read_b32 v77, v77 offset:8192
	v_lshl_add_u32 v78, v78, 6, v116
	v_med3_i32 v79, v79, s4, v189
	ds_read_b32 v78, v78 offset:8192
	v_lshl_add_u32 v79, v79, 6, v116
	ds_read_b32 v79, v79 offset:8192
	s_waitcnt lgkmcnt(3)
	v_fmac_f32_e32 v76, 0x3d800000, v134
	v_cndmask_b32_e32 v76, v190, v76, vcc
	s_waitcnt lgkmcnt(2)
	v_fmac_f32_e32 v77, 0x3d800000, v135
	v_cmp_lt_i32_e32 vcc, -1, v139
	s_waitcnt lgkmcnt(1)
	v_fmac_f32_e32 v78, 0x3d800000, v136
	s_waitcnt lgkmcnt(0)
	v_fmac_f32_e32 v79, 0x3d800000, v137
	v_cndmask_b32_e32 v77, v190, v77, vcc
	v_cmp_lt_i32_e32 vcc, -1, v140
	v_fmac_f32_e32 v80, 0x3d800000, v72
	s_nop 0
	v_cndmask_b32_e32 v78, v190, v78, vcc
	v_cmp_lt_i32_e32 vcc, -1, v141
	s_nop 1
	v_cndmask_b32_e32 v79, v190, v79, vcc
	v_cmp_lt_i32_e32 vcc, -1, v142
	v_max_f32_e32 v81, v78, v79
	s_nop 0
	v_cndmask_b32_e32 v72, v190, v80, vcc
	v_subrev_u32_e32 v80, s29, v143
	v_med3_i32 v80, v80, s4, v189
	v_lshl_add_u32 v80, v80, 6, v116
	ds_read_b32 v80, v80 offset:8192
	v_cmp_lt_i32_e32 vcc, -1, v143
	s_waitcnt lgkmcnt(0)
	v_fmac_f32_e32 v80, 0x3d800000, v73
	v_subrev_u32_e32 v73, s29, v148
	v_med3_i32 v73, v73, s4, v189
	v_lshl_add_u32 v73, v73, 6, v116
	ds_read_b32 v73, v73 offset:8192
	v_cndmask_b32_e32 v80, v190, v80, vcc
	v_cmp_lt_i32_e32 vcc, -1, v148
	s_waitcnt lgkmcnt(0)
	v_fmac_f32_e32 v73, 0x3d800000, v74
	v_cndmask_b32_e32 v74, v190, v73, vcc
	v_subrev_u32_e32 v73, s29, v149
	v_med3_i32 v73, v73, s4, v189
	v_lshl_add_u32 v73, v73, 6, v116
	ds_read_b32 v73, v73 offset:8192
	v_cmp_lt_i32_e32 vcc, -1, v149
	s_waitcnt lgkmcnt(0)
	v_fmac_f32_e32 v73, 0x3d800000, v75
	v_cndmask_b32_e32 v75, v190, v73, vcc
	s_add_i32 s2, s30, 1
	s_cmp_eq_u32 s2, 8
	s_cbranch_scc1 .Latt_nopf
	s_lshr_b32 s3, s2, 1
	s_cmp_eq_u32 s3, 2
	s_cselect_b64 vcc, -1, 0
	v_cndmask_b32_e32 v244, v127, v126, vcc
	s_cmp_eq_u32 s3, 1
	s_cselect_b64 vcc, -1, 0
	v_cndmask_b32_e32 v244, v244, v125, vcc
	s_cmp_eq_u32 s3, 0
	s_cselect_b64 vcc, -1, 0
	v_cndmask_b32_e32 v244, v244, v124, vcc
	s_bitcmp1_b32 s2, 0
	v_readfirstlane_b32 s2, v108
	v_readfirstlane_b32 s3, v109
	s_cbranch_scc1 .Latt_pf_odd
	v_readlane_b32 s0, v244, 0
	v_readlane_b32 s1, v244, 1
	v_readlane_b32 vcc_lo, v244, 2
	v_readlane_b32 vcc_hi, v244, 3
	s_max_i32 s0, s0, 0
	s_max_i32 s1, s1, 0
	s_max_i32 vcc_lo, vcc_lo, 0
	s_max_i32 vcc_hi, vcc_hi, 0
	s_sub_i32 s1, s1, s0
	s_sub_i32 vcc_hi, vcc_hi, vcc_lo
	s_lshl_b32 s0, s0, 9
	s_lshl_b32 s1, s1, 9
	s_lshl_b32 vcc_lo, vcc_lo, 9
	s_lshl_b32 vcc_hi, vcc_hi, 9
	v_add_u32_e32 v88, s0, v246
	v_add_u32_e32 v92, vcc_lo, v246
	v_mad_i32_i24 v88, v115, s1, v88
	v_mad_i32_i24 v92, v115, vcc_hi, v92
	global_load_dwordx4 v[88:91], v88, s[2:3]
	global_load_dwordx4 v[92:95], v92, s[2:3]
	v_readlane_b32 s0, v244, 4
	v_readlane_b32 s1, v244, 5
	v_readlane_b32 vcc_lo, v244, 6
	v_readlane_b32 vcc_hi, v244, 7
	s_max_i32 s0, s0, 0
	s_max_i32 s1, s1, 0
	s_max_i32 vcc_lo, vcc_lo, 0
	s_max_i32 vcc_hi, vcc_hi, 0
	s_sub_i32 s1, s1, s0
	s_sub_i32 vcc_hi, vcc_hi, vcc_lo
	s_lshl_b32 s0, s0, 9
	s_lshl_b32 s1, s1, 9
	s_lshl_b32 vcc_lo, vcc_lo, 9
	s_lshl_b32 vcc_hi, vcc_hi, 9
	v_add_u32_e32 v96, s0, v246
	v_add_u32_e32 v144, vcc_lo, v246
	v_mad_i32_i24 v96, v115, s1, v96
	v_mad_i32_i24 v144, v115, vcc_hi, v144
	global_load_dwordx4 v[96:99], v96, s[2:3]
	global_load_dwordx4 v[144:147], v144, s[2:3]
	v_readlane_b32 s0, v244, 8
	v_readlane_b32 s1, v244, 9
	v_readlane_b32 vcc_lo, v244, 10
	v_readlane_b32 vcc_hi, v244, 11
	s_max_i32 s0, s0, 0
	s_max_i32 s1, s1, 0
	s_max_i32 vcc_lo, vcc_lo, 0
	s_max_i32 vcc_hi, vcc_hi, 0
	s_sub_i32 s1, s1, s0
	s_sub_i32 vcc_hi, vcc_hi, vcc_lo
	s_lshl_b32 s0, s0, 9
	s_lshl_b32 s1, s1, 9
	s_lshl_b32 vcc_lo, vcc_lo, 9
	s_lshl_b32 vcc_hi, vcc_hi, 9
	v_add_u32_e32 v152, s0, v246
	v_add_u32_e32 v156, vcc_lo, v246
	v_mad_i32_i24 v152, v115, s1, v152
	v_mad_i32_i24 v156, v115, vcc_hi, v156
	global_load_dwordx4 v[152:155], v152, s[2:3]
	global_load_dwordx4 v[156:159], v156, s[2:3]
	v_readlane_b32 s0, v244, 12
	v_readlane_b32 s1, v244, 13
	v_readlane_b32 vcc_lo, v244, 14
	v_readlane_b32 vcc_hi, v244, 15
	s_max_i32 s0, s0, 0
	s_max_i32 s1, s1, 0
	s_max_i32 vcc_lo, vcc_lo, 0
	s_max_i32 vcc_hi, vcc_hi, 0
	s_sub_i32 s1, s1, s0
	s_sub_i32 vcc_hi, vcc_hi, vcc_lo
	s_lshl_b32 s0, s0, 9
	s_lshl_b32 s1, s1, 9
	s_lshl_b32 vcc_lo, vcc_lo, 9
	s_lshl_b32 vcc_hi, vcc_hi, 9
	v_add_u32_e32 v160, s0, v246
	v_add_u32_e32 v172, vcc_lo, v246
	v_mad_i32_i24 v160, v115, s1, v160
	v_mad_i32_i24 v172, v115, vcc_hi, v172
	global_load_dwordx4 v[160:163], v160, s[2:3]
	global_load_dwordx4 v[172:175], v172, s[2:3]
	v_readlane_b32 s0, v244, 16
	v_readlane_b32 s1, v244, 17
	v_readlane_b32 vcc_lo, v244, 18
	v_readlane_b32 vcc_hi, v244, 19
	s_max_i32 s0, s0, 0
	s_max_i32 s1, s1, 0
	s_max_i32 vcc_lo, vcc_lo, 0
	s_max_i32 vcc_hi, vcc_hi, 0
	s_sub_i32 s1, s1, s0
	s_sub_i32 vcc_hi, vcc_hi, vcc_lo
	s_lshl_b32 s0, s0, 9
	s_lshl_b32 s1, s1, 9
	s_lshl_b32 vcc_lo, vcc_lo, 9
	s_lshl_b32 vcc_hi, vcc_hi, 9
	v_add_u32_e32 v192, s0, v246
	v_add_u32_e32 v132, vcc_lo, v246
	v_mad_i32_i24 v192, v115, s1, v192
	v_mad_i32_i24 v132, v115, vcc_hi, v132
	global_load_dwordx4 v[192:195], v192, s[2:3]
	global_load_dwordx4 v[132:135], v132, s[2:3]
	v_readlane_b32 s0, v244, 20
	v_readlane_b32 s1, v244, 21
	v_readlane_b32 vcc_lo, v244, 22
	v_readlane_b32 vcc_hi, v244, 23
	s_max_i32 s0, s0, 0
	s_max_i32 s1, s1, 0
	s_max_i32 vcc_lo, vcc_lo, 0
	s_max_i32 vcc_hi, vcc_hi, 0
	s_sub_i32 s1, s1, s0
	s_sub_i32 vcc_hi, vcc_hi, vcc_lo
	s_lshl_b32 s0, s0, 9
	s_lshl_b32 s1, s1, 9
	s_lshl_b32 vcc_lo, vcc_lo, 9
	s_lshl_b32 vcc_hi, vcc_hi, 9
	v_add_u32_e32 v136, s0, v246
	v_add_u32_e32 v140, vcc_lo, v246
	v_mad_i32_i24 v136, v115, s1, v136
	v_mad_i32_i24 v140, v115, vcc_hi, v140
	global_load_dwordx4 v[136:139], v136, s[2:3]
	global_load_dwordx4 v[140:143], v140, s[2:3]
	v_readlane_b32 s0, v244, 24
	v_readlane_b32 s1, v244, 25
	v_readlane_b32 vcc_lo, v244, 26
	v_readlane_b32 vcc_hi, v244, 27
	s_max_i32 s0, s0, 0
	s_max_i32 s1, s1, 0
	s_max_i32 vcc_lo, vcc_lo, 0
	s_max_i32 vcc_hi, vcc_hi, 0
	s_sub_i32 s1, s1, s0
	s_sub_i32 vcc_hi, vcc_hi, vcc_lo
	s_lshl_b32 s0, s0, 9
	s_lshl_b32 s1, s1, 9
	s_lshl_b32 vcc_lo, vcc_lo, 9
	s_lshl_b32 vcc_hi, vcc_hi, 9
	v_add_u32_e32 v228, s0, v246
	v_add_u32_e32 v232, vcc_lo, v246
	v_mad_i32_i24 v228, v115, s1, v228
	v_mad_i32_i24 v232, v115, vcc_hi, v232
	global_load_dwordx4 v[228:231], v228, s[2:3]
	global_load_dwordx4 v[232:235], v232, s[2:3]
	v_readlane_b32 s0, v244, 28
	v_readlane_b32 s1, v244, 29
	v_readlane_b32 vcc_lo, v244, 30
	v_readlane_b32 vcc_hi, v244, 31
	s_max_i32 s0, s0, 0
	s_max_i32 s1, s1, 0
	s_max_i32 vcc_lo, vcc_lo, 0
	s_max_i32 vcc_hi, vcc_hi, 0
	s_sub_i32 s1, s1, s0
	s_sub_i32 vcc_hi, vcc_hi, vcc_lo
	s_lshl_b32 s0, s0, 9
	s_lshl_b32 s1, s1, 9
	s_lshl_b32 vcc_lo, vcc_lo, 9
	s_lshl_b32 vcc_hi, vcc_hi, 9
	v_add_u32_e32 v236, s0, v246
	v_add_u32_e32 v240, vcc_lo, v246
	v_mad_i32_i24 v236, v115, s1, v236
	v_mad_i32_i24 v240, v115, vcc_hi, v240
	global_load_dwordx4 v[236:239], v236, s[2:3]
	global_load_dwordx4 v[240:243], v240, s[2:3]
	s_branch .Latt_nopf
.Latt_pf_odd:
	v_readlane_b32 s0, v244, 32
	v_readlane_b32 s1, v244, 33
	v_readlane_b32 vcc_lo, v244, 34
	v_readlane_b32 vcc_hi, v244, 35
	s_max_i32 s0, s0, 0
	s_max_i32 s1, s1, 0
	s_max_i32 vcc_lo, vcc_lo, 0
	s_max_i32 vcc_hi, vcc_hi, 0
	s_sub_i32 s1, s1, s0
	s_sub_i32 vcc_hi, vcc_hi, vcc_lo
	s_lshl_b32 s0, s0, 9
	s_lshl_b32 s1, s1, 9
	s_lshl_b32 vcc_lo, vcc_lo, 9
	s_lshl_b32 vcc_hi, vcc_hi, 9
	v_add_u32_e32 v88, s0, v246
	v_add_u32_e32 v92, vcc_lo, v246
	v_mad_i32_i24 v88, v115, s1, v88
	v_mad_i32_i24 v92, v115, vcc_hi, v92
	global_load_dwordx4 v[88:91], v88, s[2:3]
	global_load_dwordx4 v[92:95], v92, s[2:3]
	v_readlane_b32 s0, v244, 36
	v_readlane_b32 s1, v244, 37
	v_readlane_b32 vcc_lo, v244, 38
	v_readlane_b32 vcc_hi, v244, 39
	s_max_i32 s0, s0, 0
	s_max_i32 s1, s1, 0
	s_max_i32 vcc_lo, vcc_lo, 0
	s_max_i32 vcc_hi, vcc_hi, 0
	s_sub_i32 s1, s1, s0
	s_sub_i32 vcc_hi, vcc_hi, vcc_lo
	s_lshl_b32 s0, s0, 9
	s_lshl_b32 s1, s1, 9
	s_lshl_b32 vcc_lo, vcc_lo, 9
	s_lshl_b32 vcc_hi, vcc_hi, 9
	v_add_u32_e32 v96, s0, v246
	v_add_u32_e32 v144, vcc_lo, v246
	v_mad_i32_i24 v96, v115, s1, v96
	v_mad_i32_i24 v144, v115, vcc_hi, v144
	global_load_dwordx4 v[96:99], v96, s[2:3]
	global_load_dwordx4 v[144:147], v144, s[2:3]
	v_readlane_b32 s0, v244, 40
	v_readlane_b32 s1, v244, 41
	v_readlane_b32 vcc_lo, v244, 42
	v_readlane_b32 vcc_hi, v244, 43
	s_max_i32 s0, s0, 0
	s_max_i32 s1, s1, 0
	s_max_i32 vcc_lo, vcc_lo, 0
	s_max_i32 vcc_hi, vcc_hi, 0
	s_sub_i32 s1, s1, s0
	s_sub_i32 vcc_hi, vcc_hi, vcc_lo
	s_lshl_b32 s0, s0, 9
	s_lshl_b32 s1, s1, 9
	s_lshl_b32 vcc_lo, vcc_lo, 9
	s_lshl_b32 vcc_hi, vcc_hi, 9
	v_add_u32_e32 v152, s0, v246
	v_add_u32_e32 v156, vcc_lo, v246
	v_mad_i32_i24 v152, v115, s1, v152
	v_mad_i32_i24 v156, v115, vcc_hi, v156
	global_load_dwordx4 v[152:155], v152, s[2:3]
	global_load_dwordx4 v[156:159], v156, s[2:3]
	v_readlane_b32 s0, v244, 44
	v_readlane_b32 s1, v244, 45
	v_readlane_b32 vcc_lo, v244, 46
	v_readlane_b32 vcc_hi, v244, 47
	s_max_i32 s0, s0, 0
	s_max_i32 s1, s1, 0
	s_max_i32 vcc_lo, vcc_lo, 0
	s_max_i32 vcc_hi, vcc_hi, 0
	s_sub_i32 s1, s1, s0
	s_sub_i32 vcc_hi, vcc_hi, vcc_lo
	s_lshl_b32 s0, s0, 9
	s_lshl_b32 s1, s1, 9
	s_lshl_b32 vcc_lo, vcc_lo, 9
	s_lshl_b32 vcc_hi, vcc_hi, 9
	v_add_u32_e32 v160, s0, v246
	v_add_u32_e32 v172, vcc_lo, v246
	v_mad_i32_i24 v160, v115, s1, v160
	v_mad_i32_i24 v172, v115, vcc_hi, v172
	global_load_dwordx4 v[160:163], v160, s[2:3]
	global_load_dwordx4 v[172:175], v172, s[2:3]
	v_readlane_b32 s0, v244, 48
	v_readlane_b32 s1, v244, 49
	v_readlane_b32 vcc_lo, v244, 50
	v_readlane_b32 vcc_hi, v244, 51
	s_max_i32 s0, s0, 0
	s_max_i32 s1, s1, 0
	s_max_i32 vcc_lo, vcc_lo, 0
	s_max_i32 vcc_hi, vcc_hi, 0
	s_sub_i32 s1, s1, s0
	s_sub_i32 vcc_hi, vcc_hi, vcc_lo
	s_lshl_b32 s0, s0, 9
	s_lshl_b32 s1, s1, 9
	s_lshl_b32 vcc_lo, vcc_lo, 9
	s_lshl_b32 vcc_hi, vcc_hi, 9
	v_add_u32_e32 v192, s0, v246
	v_add_u32_e32 v132, vcc_lo, v246
	v_mad_i32_i24 v192, v115, s1, v192
	v_mad_i32_i24 v132, v115, vcc_hi, v132
	global_load_dwordx4 v[192:195], v192, s[2:3]
	global_load_dwordx4 v[132:135], v132, s[2:3]
	v_readlane_b32 s0, v244, 52
	v_readlane_b32 s1, v244, 53
	v_readlane_b32 vcc_lo, v244, 54
	v_readlane_b32 vcc_hi, v244, 55
	s_max_i32 s0, s0, 0
	s_max_i32 s1, s1, 0
	s_max_i32 vcc_lo, vcc_lo, 0
	s_max_i32 vcc_hi, vcc_hi, 0
	s_sub_i32 s1, s1, s0
	s_sub_i32 vcc_hi, vcc_hi, vcc_lo
	s_lshl_b32 s0, s0, 9
	s_lshl_b32 s1, s1, 9
	s_lshl_b32 vcc_lo, vcc_lo, 9
	s_lshl_b32 vcc_hi, vcc_hi, 9
	v_add_u32_e32 v136, s0, v246
	v_add_u32_e32 v140, vcc_lo, v246
	v_mad_i32_i24 v136, v115, s1, v136
	v_mad_i32_i24 v140, v115, vcc_hi, v140
	global_load_dwordx4 v[136:139], v136, s[2:3]
	global_load_dwordx4 v[140:143], v140, s[2:3]
	v_readlane_b32 s0, v244, 56
	v_readlane_b32 s1, v244, 57
	v_readlane_b32 vcc_lo, v244, 58
	v_readlane_b32 vcc_hi, v244, 59
	s_max_i32 s0, s0, 0
	s_max_i32 s1, s1, 0
	s_max_i32 vcc_lo, vcc_lo, 0
	s_max_i32 vcc_hi, vcc_hi, 0
	s_sub_i32 s1, s1, s0
	s_sub_i32 vcc_hi, vcc_hi, vcc_lo
	s_lshl_b32 s0, s0, 9
	s_lshl_b32 s1, s1, 9
	s_lshl_b32 vcc_lo, vcc_lo, 9
	s_lshl_b32 vcc_hi, vcc_hi, 9
	v_add_u32_e32 v228, s0, v246
	v_add_u32_e32 v232, vcc_lo, v246
	v_mad_i32_i24 v228, v115, s1, v228
	v_mad_i32_i24 v232, v115, vcc_hi, v232
	global_load_dwordx4 v[228:231], v228, s[2:3]
	global_load_dwordx4 v[232:235], v232, s[2:3]
	v_readlane_b32 s0, v244, 60
	v_readlane_b32 s1, v244, 61
	v_readlane_b32 vcc_lo, v244, 62
	v_readlane_b32 vcc_hi, v244, 63
	s_max_i32 s0, s0, 0
	s_max_i32 s1, s1, 0
	s_max_i32 vcc_lo, vcc_lo, 0
	s_max_i32 vcc_hi, vcc_hi, 0
	s_sub_i32 s1, s1, s0
	s_sub_i32 vcc_hi, vcc_hi, vcc_lo
	s_lshl_b32 s0, s0, 9
	s_lshl_b32 s1, s1, 9
	s_lshl_b32 vcc_lo, vcc_lo, 9
	s_lshl_b32 vcc_hi, vcc_hi, 9
	v_add_u32_e32 v236, s0, v246
	v_add_u32_e32 v240, vcc_lo, v246
	v_mad_i32_i24 v236, v115, s1, v236
	v_mad_i32_i24 v240, v115, vcc_hi, v240
	global_load_dwordx4 v[236:239], v236, s[2:3]
	global_load_dwordx4 v[240:243], v240, s[2:3]
.Latt_nopf:
	v_max_f32_e32 v82, v74, v75
	v_max_f32_e32 v73, v76, v77
	v_max3_f32 v82, v72, v80, v82
	v_max3_f32 v73, v73, v81, v82
	v_mov_b32_e32 v81, v73
	s_nop 1
	v_permlane16_swap_b32 v81, v73
	v_max_f32_e32 v73, v73, v81
	v_mov_b32_e32 v81, v73
	s_nop 1
	v_permlane32_swap_b32 v81, v73
	v_max3_f32 v73, v128, v73, v81
	v_sub_f32_e32 v72, v72, v73
	v_mul_f32_e32 v72, 0x3fb8aa3b, v72
	v_sub_f32_e32 v76, v76, v73
	v_exp_f32_e32 v82, v72
	v_sub_f32_e32 v72, v80, v73
	v_mul_f32_e32 v76, 0x3fb8aa3b, v76
	v_sub_f32_e32 v77, v77, v73
	v_mul_f32_e32 v72, 0x3fb8aa3b, v72
	v_exp_f32_e32 v76, v76
	v_mul_f32_e32 v77, 0x3fb8aa3b, v77
	v_sub_f32_e32 v78, v78, v73
	v_exp_f32_e32 v80, v72
	v_sub_f32_e32 v72, v74, v73
	v_exp_f32_e32 v77, v77
	v_mul_f32_e32 v78, 0x3fb8aa3b, v78
	v_sub_f32_e32 v79, v79, v73
	v_mul_f32_e32 v72, 0x3fb8aa3b, v72
	v_exp_f32_e32 v78, v78
	v_mul_f32_e32 v79, 0x3fb8aa3b, v79
	v_exp_f32_e32 v83, v72
	v_sub_f32_e32 v72, v75, v73
	v_exp_f32_e32 v79, v79
	v_mul_f32_e32 v72, 0x3fb8aa3b, v72
	v_exp_f32_e32 v84, v72
	v_add_f32_e32 v72, 0, v76
	v_add_f32_e32 v72, v77, v72
	v_add_f32_e32 v72, v78, v72
	v_sub_f32_e32 v81, v128, v73
	v_add_f32_e32 v72, v79, v72
	v_mul_f32_e32 v81, 0x3fb8aa3b, v81
	v_add_f32_e32 v72, v82, v72
	v_exp_f32_e32 v86, v81
	v_add_f32_e32 v72, v80, v72
	v_add_f32_e32 v72, v83, v72
	v_cvt_pk_bf16_f32 v74, v76, v77
	v_cvt_pk_bf16_f32 v75, v78, v79
	v_cvt_pk_bf16_f32 v76, v82, v80
	v_cvt_pk_bf16_f32 v77, v83, v84
	ds_read_b64_tr_b16 v[80:81], v119 offset:8448
	ds_read_b64_tr_b16 v[78:79], v119
	ds_read_b64_tr_b16 v[82:83], v119 offset:32
	v_pk_mul_f32 v[70:71], v[70:71], v[86:87] op_sel_hi:[1,0]
	v_pk_mul_f32 v[68:69], v[68:69], v[86:87] op_sel_hi:[1,0]
	v_add_f32_e32 v72, v84, v72
	ds_read_b64_tr_b16 v[84:85], v119 offset:8480
	s_waitcnt lgkmcnt(2)
	v_mfma_f32_16x16x32_bf16 v[68:71], v[78:81], v[74:77], v[68:71]
	ds_read_b64_tr_b16 v[78:79], v119 offset:64
	ds_read_b64_tr_b16 v[80:81], v119 offset:8512
	v_pk_mul_f32 v[66:67], v[66:67], v[86:87] op_sel_hi:[1,0]
	v_pk_mul_f32 v[64:65], v[64:65], v[86:87] op_sel_hi:[1,0]
	v_pk_mul_f32 v[62:63], v[62:63], v[86:87] op_sel_hi:[1,0]
	v_pk_mul_f32 v[60:61], v[60:61], v[86:87] op_sel_hi:[1,0]
	s_waitcnt lgkmcnt(0)
	v_mfma_f32_16x16x32_bf16 v[64:67], v[78:81], v[74:77], v[64:67]
	ds_read_b64_tr_b16 v[78:79], v119 offset:96
	ds_read_b64_tr_b16 v[80:81], v119 offset:8544
	v_pk_mul_f32 v[26:27], v[26:27], v[86:87] op_sel_hi:[1,0]
	v_pk_mul_f32 v[24:25], v[24:25], v[86:87] op_sel_hi:[1,0]
	s_waitcnt lgkmcnt(0)
	v_mfma_f32_16x16x32_bf16 v[60:63], v[78:81], v[74:77], v[60:63]
	v_mul_f32_e64 v58, v58, v86
	v_mul_f32_e64 v59, v59, v86
	v_pk_mul_f32 v[56:57], v[56:57], v[86:87] op_sel_hi:[1,0]
	v_pk_mul_f32 v[50:51], v[50:51], v[86:87] op_sel_hi:[1,0]
	v_mfma_f32_16x16x32_bf16 v[24:27], v[82:85], v[74:77], v[24:27]
	ds_read_b64_tr_b16 v[80:81], v119 offset:8576
	ds_read_b64_tr_b16 v[78:79], v119 offset:128
	ds_read_b64_tr_b16 v[82:83], v119 offset:160
	ds_read_b64_tr_b16 v[84:85], v119 offset:8608
	v_pk_mul_f32 v[48:49], v[48:49], v[86:87] op_sel_hi:[1,0]
	s_waitcnt lgkmcnt(2)
	v_mfma_f32_16x16x32_bf16 v[56:59], v[78:81], v[74:77], v[56:59]
	ds_read_b64_tr_b16 v[78:79], v119 offset:192
	ds_read_b64_tr_b16 v[80:81], v119 offset:8640
	v_pk_mul_f32 v[54:55], v[54:55], v[86:87] op_sel_hi:[1,0]
	v_pk_mul_f32 v[52:53], v[52:53], v[86:87] op_sel_hi:[1,0]
	s_waitcnt lgkmcnt(0)
	v_mfma_f32_16x16x32_bf16 v[48:51], v[78:81], v[74:77], v[48:51]
	ds_read_b64_tr_b16 v[78:79], v119 offset:224
	ds_read_b64_tr_b16 v[80:81], v119 offset:8672
	v_pk_mul_f32 v[46:47], v[46:47], v[86:87] op_sel_hi:[1,0]
	v_pk_mul_f32 v[44:45], v[44:45], v[86:87] op_sel_hi:[1,0]
	v_mfma_f32_16x16x32_bf16 v[52:55], v[82:85], v[74:77], v[52:55]
	v_mul_f32_e64 v42, v42, v86
	v_mul_f32_e64 v43, v43, v86
	v_pk_mul_f32 v[40:41], v[40:41], v[86:87] op_sel_hi:[1,0]
	v_pk_mul_f32 v[22:23], v[22:23], v[86:87] op_sel_hi:[1,0]
	s_waitcnt lgkmcnt(0)
	v_mfma_f32_16x16x32_bf16 v[44:47], v[78:81], v[74:77], v[44:47]
	ds_read_b64_tr_b16 v[80:81], v119 offset:8704
	ds_read_b64_tr_b16 v[78:79], v119 offset:256
	ds_read_b64_tr_b16 v[82:83], v119 offset:288
	ds_read_b64_tr_b16 v[84:85], v119 offset:8736
	v_pk_mul_f32 v[20:21], v[20:21], v[86:87] op_sel_hi:[1,0]
	s_waitcnt lgkmcnt(2)
	v_mfma_f32_16x16x32_bf16 v[40:43], v[78:81], v[74:77], v[40:43]
	ds_read_b64_tr_b16 v[78:79], v119 offset:320
	ds_read_b64_tr_b16 v[80:81], v119 offset:8768
	v_pk_mul_f32 v[30:31], v[30:31], v[86:87] op_sel_hi:[1,0]
	v_pk_mul_f32 v[28:29], v[28:29], v[86:87] op_sel_hi:[1,0]
	s_waitcnt lgkmcnt(0)
	v_mfma_f32_16x16x32_bf16 v[20:23], v[78:81], v[74:77], v[20:23]
	ds_read_b64_tr_b16 v[78:79], v119 offset:352
	ds_read_b64_tr_b16 v[80:81], v119 offset:8800
	v_pk_mul_f32 v[18:19], v[18:19], v[86:87] op_sel_hi:[1,0]
	v_pk_mul_f32 v[16:17], v[16:17], v[86:87] op_sel_hi:[1,0]
	v_mfma_f32_16x16x32_bf16 v[28:31], v[82:85], v[74:77], v[28:31]
	v_mul_f32_e64 v14, v14, v86
	v_mul_f32_e64 v15, v15, v86
	v_pk_mul_f32 v[12:13], v[12:13], v[86:87] op_sel_hi:[1,0]
	v_pk_mul_f32 v[6:7], v[6:7], v[86:87] op_sel_hi:[1,0]
	s_waitcnt lgkmcnt(0)
	v_mfma_f32_16x16x32_bf16 v[16:19], v[78:81], v[74:77], v[16:19]
	ds_read_b64_tr_b16 v[80:81], v119 offset:8832
	ds_read_b64_tr_b16 v[78:79], v119 offset:384
	ds_read_b64_tr_b16 v[82:83], v119 offset:416
	ds_read_b64_tr_b16 v[84:85], v119 offset:8864
	v_pk_mul_f32 v[4:5], v[4:5], v[86:87] op_sel_hi:[1,0]
	s_waitcnt lgkmcnt(2)
	v_mfma_f32_16x16x32_bf16 v[12:15], v[78:81], v[74:77], v[12:15]
	ds_read_b64_tr_b16 v[78:79], v119 offset:448
	ds_read_b64_tr_b16 v[80:81], v119 offset:8896
	v_pk_mul_f32 v[10:11], v[10:11], v[86:87] op_sel_hi:[1,0]
	v_pk_mul_f32 v[8:9], v[8:9], v[86:87] op_sel_hi:[1,0]
	s_waitcnt lgkmcnt(0)
	v_mfma_f32_16x16x32_bf16 v[4:7], v[78:81], v[74:77], v[4:7]
	ds_read_b64_tr_b16 v[78:79], v119 offset:480
	ds_read_b64_tr_b16 v[80:81], v119 offset:8928
	v_pk_mul_f32 v[2:3], v[2:3], v[86:87] op_sel_hi:[1,0]
	v_pk_mul_f32 v[0:1], v[0:1], v[86:87] op_sel_hi:[1,0]
	v_mfma_f32_16x16x32_bf16 v[8:11], v[82:85], v[74:77], v[8:11]
	s_waitcnt lgkmcnt(0)
	v_fmac_f32_e32 v72, v129, v86
	s_waitcnt lgkmcnt(0)
	v_mfma_f32_16x16x32_bf16 v[0:3], v[78:81], v[74:77], v[0:3]
	v_mov_b32_e32 v128, v73
	s_add_i32 s30, s30, 1
	s_add_i32 s28, s28, 32
	s_cmp_eq_u32 s30, 8
	s_cbranch_scc0 .LBB0_136
	ds_bpermute_b32 v73, v113, v72
	v_mov_b32_e32 v124, v123
	v_mov_b32_e32 v125, v122
	v_mov_b32_e32 v126, v121
	v_mov_b32_e32 v127, v120
	s_waitcnt lgkmcnt(0)
	v_add_f32_e32 v72, v72, v73
	ds_bpermute_b32 v73, v114, v72
	s_mov_b32 s2, s25
	s_waitcnt lgkmcnt(0)
	v_add_f32_e32 v72, v72, v73
	v_div_scale_f32 v73, s[0:1], v72, v72, 1.0
	v_rcp_f32_e32 v74, v73
	s_lshl_b64 s[0:1], s[76:77], 13
	s_mov_b32 s76, s38
	v_fma_f32 v75, -v73, v74, 1.0
	v_fmac_f32_e32 v74, v75, v74
	v_div_scale_f32 v75, vcc, 1.0, v72, 1.0
	v_mul_f32_e32 v76, v75, v74
	v_fma_f32 v77, -v73, v76, v75
	v_fmac_f32_e32 v76, v77, v74
	v_fma_f32 v73, -v73, v76, v75
	v_div_fmas_f32 v73, v73, v74, v76
	v_div_fixup_f32 v72, v73, v72, 1.0
	v_pk_mul_f32 v[24:25], v[24:25], v[72:73] op_sel_hi:[1,0]
	v_pk_mul_f32 v[26:27], v[26:27], v[72:73] op_sel_hi:[1,0]
	v_lshl_add_u64 v[74:75], v[104:105], 0, s[0:1]
	v_cvt_pk_bf16_f32 v24, v24, v25
	v_cvt_pk_bf16_f32 v25, v26, v27
	global_store_dwordx2 v[74:75], v[24:25], off offset:32
	v_pk_mul_f32 v[24:25], v[64:65], v[72:73] op_sel_hi:[1,0]
	v_pk_mul_f32 v[26:27], v[66:67], v[72:73] op_sel_hi:[1,0]
	v_cvt_pk_bf16_f32 v24, v24, v25
	v_cvt_pk_bf16_f32 v25, v26, v27
	global_store_dwordx2 v[74:75], v[24:25], off offset:64
	v_pk_mul_f32 v[24:25], v[60:61], v[72:73] op_sel_hi:[1,0]
	v_pk_mul_f32 v[26:27], v[62:63], v[72:73] op_sel_hi:[1,0]
	v_cvt_pk_bf16_f32 v24, v24, v25
	v_cvt_pk_bf16_f32 v25, v26, v27
	global_store_dwordx2 v[74:75], v[24:25], off offset:96
	v_pk_mul_f32 v[24:25], v[56:57], v[72:73] op_sel_hi:[1,0]
	v_pk_mul_f32 v[26:27], v[58:59], v[72:73] op_sel_hi:[1,0]
	v_cvt_pk_bf16_f32 v24, v24, v25
	v_cvt_pk_bf16_f32 v25, v26, v27
	global_store_dwordx2 v[74:75], v[24:25], off offset:128
	v_pk_mul_f32 v[24:25], v[52:53], v[72:73] op_sel_hi:[1,0]
	v_pk_mul_f32 v[26:27], v[54:55], v[72:73] op_sel_hi:[1,0]
	v_cvt_pk_bf16_f32 v24, v24, v25
	v_cvt_pk_bf16_f32 v25, v26, v27
	global_store_dwordx2 v[74:75], v[24:25], off offset:160
	v_pk_mul_f32 v[24:25], v[48:49], v[72:73] op_sel_hi:[1,0]
	v_pk_mul_f32 v[26:27], v[50:51], v[72:73] op_sel_hi:[1,0]
	v_cvt_pk_bf16_f32 v24, v24, v25
	v_cvt_pk_bf16_f32 v25, v26, v27
	global_store_dwordx2 v[74:75], v[24:25], off offset:192
	v_pk_mul_f32 v[24:25], v[44:45], v[72:73] op_sel_hi:[1,0]
	v_pk_mul_f32 v[26:27], v[46:47], v[72:73] op_sel_hi:[1,0]
	v_cvt_pk_bf16_f32 v24, v24, v25
	v_cvt_pk_bf16_f32 v25, v26, v27
	global_store_dwordx2 v[74:75], v[24:25], off offset:224
	v_pk_mul_f32 v[24:25], v[40:41], v[72:73] op_sel_hi:[1,0]
	v_pk_mul_f32 v[26:27], v[42:43], v[72:73] op_sel_hi:[1,0]
	v_cvt_pk_bf16_f32 v24, v24, v25
	v_cvt_pk_bf16_f32 v25, v26, v27
	v_pk_mul_f32 v[68:69], v[68:69], v[72:73] op_sel_hi:[1,0]
	v_pk_mul_f32 v[70:71], v[70:71], v[72:73] op_sel_hi:[1,0]
	global_store_dwordx2 v[74:75], v[24:25], off offset:256
	v_pk_mul_f32 v[24:25], v[28:29], v[72:73] op_sel_hi:[1,0]
	v_pk_mul_f32 v[26:27], v[30:31], v[72:73] op_sel_hi:[1,0]
	v_pk_mul_f32 v[20:21], v[20:21], v[72:73] op_sel_hi:[1,0]
	v_pk_mul_f32 v[22:23], v[22:23], v[72:73] op_sel_hi:[1,0]
	v_pk_mul_f32 v[16:17], v[16:17], v[72:73] op_sel_hi:[1,0]
	v_pk_mul_f32 v[18:19], v[18:19], v[72:73] op_sel_hi:[1,0]
	v_pk_mul_f32 v[12:13], v[12:13], v[72:73] op_sel_hi:[1,0]
	v_pk_mul_f32 v[14:15], v[14:15], v[72:73] op_sel_hi:[1,0]
	v_pk_mul_f32 v[8:9], v[8:9], v[72:73] op_sel_hi:[1,0]
	v_pk_mul_f32 v[10:11], v[10:11], v[72:73] op_sel_hi:[1,0]
	v_pk_mul_f32 v[4:5], v[4:5], v[72:73] op_sel_hi:[1,0]
	v_pk_mul_f32 v[6:7], v[6:7], v[72:73] op_sel_hi:[1,0]
	v_pk_mul_f32 v[0:1], v[0:1], v[72:73] op_sel_hi:[1,0]
	v_pk_mul_f32 v[2:3], v[2:3], v[72:73] op_sel_hi:[1,0]
	v_cvt_pk_bf16_f32 v68, v68, v69
	v_cvt_pk_bf16_f32 v69, v70, v71
	v_cvt_pk_bf16_f32 v24, v24, v25
	v_cvt_pk_bf16_f32 v25, v26, v27
	v_cvt_pk_bf16_f32 v20, v20, v21
	v_cvt_pk_bf16_f32 v21, v22, v23
	v_cvt_pk_bf16_f32 v16, v16, v17
	v_cvt_pk_bf16_f32 v17, v18, v19
	v_cvt_pk_bf16_f32 v12, v12, v13
	v_cvt_pk_bf16_f32 v13, v14, v15
	v_cvt_pk_bf16_f32 v8, v8, v9
	v_cvt_pk_bf16_f32 v9, v10, v11
	v_cvt_pk_bf16_f32 v4, v4, v5
	v_cvt_pk_bf16_f32 v5, v6, v7
	v_cvt_pk_bf16_f32 v0, v0, v1
	v_cvt_pk_bf16_f32 v1, v2, v3
	s_and_b64 vcc, exec, s[40:41]
	global_store_dwordx2 v[74:75], v[68:69], off
	global_store_dwordx2 v[74:75], v[24:25], off offset:288
	global_store_dwordx2 v[74:75], v[20:21], off offset:320
	global_store_dwordx2 v[74:75], v[16:17], off offset:352
	global_store_dwordx2 v[74:75], v[12:13], off offset:384
	global_store_dwordx2 v[74:75], v[8:9], off offset:416
	global_store_dwordx2 v[74:75], v[4:5], off offset:448
	global_store_dwordx2 v[74:75], v[0:1], off offset:480
	s_cbranch_vccz .LBB0_128
